# attention S2 (exp+PV) hand-scheduled: each V fragment in its own register quad, LDS reads issued >=2 MFMAs ahead, derived lgkmcnt (on top of ccdma + trims)
# speedup vs baseline: 1.0191x; 1.0191x over previous
; #define LOADV(dst, ks_) do { _Pragma("unroll") for (int dvb = 0; dvb < 4; ++dvb) { dst[2 * dvb] = vtr(vp + dvb * 4096 + (ks_) * 1024); dst[2 * dvb + 1] = vtr(vp + dvb * 4096 + (ks_) * 1024 + 512); } } while (0)
; #define MF4(src, pfrag) do { _Pragma("unroll") for (int dvb = 0; dvb < 4; ++dvb) { \
;         const bf16x8 vf_ = __builtin_shufflevector(src[2 * dvb], src[2 * dvb + 1], 0, 1, 2, 3, 4, 5, 6, 7); o[dvb] = MFMA32(vf_, pfrag, o[dvb]); } } while (0)
; #define EXPQ(S, lo_, RS, PF) do { _Pragma("unroll") for (int i = lo_; i < lo_ + 8; ++i) { S[i] = ex2(S[i]); RS += S[i]; } \
;               u32x4 w_; w_.x = pk2(S[lo_], S[lo_ + 1]); w_.y = pk2(S[lo_ + 2], S[lo_ + 3]); w_.z = pk2(S[lo_ + 4], S[lo_ + 5]); w_.w = pk2(S[lo_ + 6], S[lo_ + 7]); PF = __builtin_bit_cast(bf16x8, w_); } while (0)
; DI void attn_unit(const Params& p, int bh, int qb, char* lds, float lam, int tid, int lane, int wid, const bool build_tab) {
;     ...
;             EXPQ(s0, 0, rs0, pf[0]);
;             LOADV(vb, 1);
;             MF4(va, pf[0]);
;             EXPQ(s0, 8, rs1, pf[1]);
;             LOADV(va, 2);
;             MF4(vb, pf[1]);
;             EXPQ(s1, 0, rs0, pf[2]);
;             LOADV(vb, 3);
;             MF4(va, pf[2]);
;             EXPQ(s1, 8, rs1, pf[3]);
;             MF4(vb, pf[3]);
;             l += rs0 + rs1;
.LBB0_359:
	ds_read_b64_tr_b16 v[242:243], v220 offset:21504
	ds_read_b64_tr_b16 v[244:245], v220 offset:22016
	ds_read_b64_tr_b16 v[246:247], v220 offset:25600
	ds_read_b64_tr_b16 v[248:249], v220 offset:26112
	v_exp_f32_e32 v222, v96
	v_exp_f32_e32 v224, v97
	v_exp_f32_e32 v226, v98
	v_exp_f32_e32 v228, v99
	v_exp_f32_e32 v230, v100
	v_exp_f32_e32 v232, v101
	v_exp_f32_e32 v234, v102
	v_exp_f32_e32 v236, v103
	v_cvt_pk_bf16_f32 v96, v222, v224
	v_cvt_pk_bf16_f32 v97, v226, v228
	v_cvt_pk_bf16_f32 v98, v230, v232
	v_cvt_pk_bf16_f32 v99, v234, v236
	ds_read_b64_tr_b16 v[100:101], v220 offset:17408
	ds_read_b64_tr_b16 v[102:103], v220 offset:17920
	s_waitcnt lgkmcnt(12)
	v_mfma_f32_32x32x16_bf16 v[48:63], v[140:143], v[96:99], v[48:63]
	ds_read_b64_tr_b16 v[250:251], v220 offset:29696
	ds_read_b64_tr_b16 v[252:253], v220 offset:30208
	v_exp_f32_e32 v223, v104
	v_exp_f32_e32 v225, v105
	v_exp_f32_e32 v227, v106
	v_add_f32_e32 v221, v224, v222
	s_waitcnt lgkmcnt(12)
	v_mfma_f32_32x32x16_bf16 v[32:47], v[136:139], v[96:99], v[32:47]
	v_exp_f32_e32 v229, v107
	v_exp_f32_e32 v231, v108
	v_exp_f32_e32 v233, v109
	v_add_f32_e32 v221, v226, v221
	s_waitcnt lgkmcnt(10)
	v_mfma_f32_32x32x16_bf16 v[16:31], v[132:135], v[96:99], v[16:31]
	v_exp_f32_e32 v235, v110
	v_exp_f32_e32 v237, v111
	v_add_f32_e32 v221, v228, v221
	v_add_f32_e32 v221, v230, v221
	ds_read_b64_tr_b16 v[104:105], v220 offset:18432
	ds_read_b64_tr_b16 v[106:107], v220 offset:18944
	ds_read_b64_tr_b16 v[108:109], v220 offset:19456
	ds_read_b64_tr_b16 v[110:111], v220 offset:19968
	s_waitcnt lgkmcnt(12)
	v_mfma_f32_32x32x16_bf16 v[0:15], v[128:131], v[96:99], v[0:15]
	ds_read_b64_tr_b16 v[128:129], v220 offset:26624
	ds_read_b64_tr_b16 v[130:131], v220 offset:27136
	v_cvt_pk_bf16_f32 v96, v223, v225
	v_cvt_pk_bf16_f32 v97, v227, v229
	v_cvt_pk_bf16_f32 v98, v231, v233
	v_cvt_pk_bf16_f32 v99, v235, v237
	v_exp_f32_e32 v140, v84
	v_exp_f32_e32 v142, v85
	s_waitcnt lgkmcnt(8)
	v_mfma_f32_32x32x16_bf16 v[48:63], v[100:103], v[96:99], v[48:63]
	v_exp_f32_e32 v238, v86
	v_exp_f32_e32 v240, v87
	v_add_f32_e32 v221, v232, v221
	ds_read_b64_tr_b16 v[84:85], v220 offset:22528
	ds_read_b64_tr_b16 v[86:87], v220 offset:23040
	v_exp_f32_e32 v136, v82
	s_waitcnt lgkmcnt(14)
	v_mfma_f32_32x32x16_bf16 v[32:47], v[242:245], v[96:99], v[32:47]
	ds_read_b64_tr_b16 v[242:243], v220 offset:23552
	ds_read_b64_tr_b16 v[244:245], v220 offset:24064
	v_exp_f32_e32 v138, v83
	v_exp_f32_e32 v132, v80
	v_exp_f32_e32 v134, v81
	v_add_f32_e32 v221, v234, v221
	s_waitcnt lgkmcnt(14)
	v_mfma_f32_32x32x16_bf16 v[16:31], v[246:249], v[96:99], v[16:31]
	ds_read_b64_tr_b16 v[246:247], v220 offset:27648
	ds_read_b64_tr_b16 v[248:249], v220 offset:28160
	v_cvt_pk_bf16_f32 v80, v132, v134
	v_cvt_pk_bf16_f32 v81, v136, v138
	v_cvt_pk_bf16_f32 v82, v140, v142
	v_cvt_pk_bf16_f32 v83, v238, v240
	v_exp_f32_e32 v133, v88
	v_exp_f32_e32 v135, v89
	s_waitcnt lgkmcnt(12)
	v_mfma_f32_32x32x16_bf16 v[0:15], v[250:253], v[96:99], v[0:15]
	ds_read_b64_tr_b16 v[250:251], v220 offset:31744
	ds_read_b64_tr_b16 v[252:253], v220 offset:32256
	v_exp_f32_e32 v137, v90
	v_exp_f32_e32 v139, v91
	v_add_f32_e32 v221, v236, v221
	ds_read_b64_tr_b16 v[88:89], v220 offset:30720
	ds_read_b64_tr_b16 v[90:91], v220 offset:31232
	v_exp_f32_e32 v141, v92
	s_waitcnt lgkmcnt(14)
	v_mfma_f32_32x32x16_bf16 v[48:63], v[104:107], v[80:83], v[48:63]
	v_exp_f32_e32 v143, v93
	v_exp_f32_e32 v239, v94
	v_exp_f32_e32 v241, v95
	v_add_f32_e32 v221, v132, v221
	s_waitcnt lgkmcnt(8)
	v_mfma_f32_32x32x16_bf16 v[32:47], v[84:87], v[80:83], v[32:47]
	v_add_f32_e32 v93, v225, v223
	v_add_f32_e32 v221, v134, v221
	v_add_f32_e32 v93, v227, v93
	v_add_f32_e32 v221, v136, v221
	v_add_f32_e32 v93, v229, v93
	v_add_f32_e32 v221, v138, v221
	s_waitcnt lgkmcnt(10)
	v_mfma_f32_32x32x16_bf16 v[16:31], v[128:131], v[80:83], v[16:31]
	v_add_f32_e32 v93, v231, v93
	v_add_f32_e32 v221, v140, v221
	v_add_f32_e32 v93, v233, v93
	v_add_f32_e32 v221, v142, v221
	v_add_f32_e32 v93, v235, v93
	v_add_f32_e32 v221, v238, v221
	v_add_f32_e32 v93, v237, v93
	s_waitcnt lgkmcnt(0)
	v_mfma_f32_32x32x16_bf16 v[0:15], v[88:91], v[80:83], v[0:15]
	v_cvt_pk_bf16_f32 v80, v133, v135
	v_cvt_pk_bf16_f32 v81, v137, v139
	v_cvt_pk_bf16_f32 v82, v141, v143
	v_cvt_pk_bf16_f32 v83, v239, v241
	v_add_f32_e32 v221, v240, v221
	v_add_f32_e32 v93, v133, v93
	s_waitcnt lgkmcnt(12)
	v_mfma_f32_32x32x16_bf16 v[48:63], v[108:111], v[80:83], v[48:63]
	v_add_f32_e32 v93, v135, v93
	v_add_f32_e32 v93, v137, v93
	s_waitcnt lgkmcnt(6)
	v_mfma_f32_32x32x16_bf16 v[32:47], v[242:245], v[80:83], v[32:47]
	v_add_f32_e32 v93, v139, v93
	v_add_f32_e32 v93, v141, v93
	s_waitcnt lgkmcnt(4)
	v_mfma_f32_32x32x16_bf16 v[16:31], v[246:249], v[80:83], v[16:31]
	v_add_f32_e32 v93, v143, v93
	v_add_f32_e32 v93, v239, v93
	s_waitcnt lgkmcnt(2)
	v_mfma_f32_32x32x16_bf16 v[0:15], v[250:253], v[80:83], v[0:15]
	v_add_f32_e32 v93, v241, v93
	v_add_f32_e32 v221, v221, v93
	v_add_f32_e32 v146, v146, v221

; #define LOADV(dst, ks_) do { _Pragma("unroll") for (int dvb = 0; dvb < 4; ++dvb) { dst[2 * dvb] = vtr(vp + dvb * 4096 + (ks_) * 1024); dst[2 * dvb + 1] = vtr(vp + dvb * 4096 + (ks_) * 1024 + 512); } } while (0)
; #define MF4(src, pfrag) do { _Pragma("unroll") for (int dvb = 0; dvb < 4; ++dvb) { \
;         const bf16x8 vf_ = __builtin_shufflevector(src[2 * dvb], src[2 * dvb + 1], 0, 1, 2, 3, 4, 5, 6, 7); o[dvb] = MFMA32(vf_, pfrag, o[dvb]); } } while (0)
; #define EXPQ(S, lo_, RS, PF) do { _Pragma("unroll") for (int i = lo_; i < lo_ + 8; ++i) { S[i] = ex2(S[i]); RS += S[i]; } \
;               u32x4 w_; w_.x = pk2(S[lo_], S[lo_ + 1]); w_.y = pk2(S[lo_ + 2], S[lo_ + 3]); w_.z = pk2(S[lo_ + 4], S[lo_ + 5]); w_.w = pk2(S[lo_ + 6], S[lo_ + 7]); PF = __builtin_bit_cast(bf16x8, w_); } while (0)
; DI void attn_unit(const Params& p, int bh, int qb, char* lds, float lam, int tid, int lane, int wid, const bool build_tab) {
;     ...
;             EXPQ(s0, 0, rs0, pf[0]);
;             LOADV(vb, 1);
;             MF4(va, pf[0]);
;             EXPQ(s0, 8, rs1, pf[1]);
;             LOADV(va, 2);
;             MF4(vb, pf[1]);
;             EXPQ(s1, 0, rs0, pf[2]);
;             LOADV(vb, 3);
;             MF4(va, pf[2]);
;             EXPQ(s1, 8, rs1, pf[3]);
;             MF4(vb, pf[3]);
;             l += rs0 + rs1;
.LBB0_379:
	ds_read_b64_tr_b16 v[230:231], v177 offset:21504
	ds_read_b64_tr_b16 v[232:233], v177 offset:22016
	ds_read_b64_tr_b16 v[234:235], v177 offset:25600
	ds_read_b64_tr_b16 v[236:237], v177 offset:26112
	v_exp_f32_e32 v178, v96
	v_exp_f32_e32 v180, v97
	v_exp_f32_e32 v182, v98
	v_exp_f32_e32 v184, v99
	v_exp_f32_e32 v186, v100
	v_exp_f32_e32 v188, v101
	v_exp_f32_e32 v190, v102
	v_exp_f32_e32 v192, v103
	v_cvt_pk_bf16_f32 v96, v178, v180
	v_cvt_pk_bf16_f32 v97, v182, v184
	v_cvt_pk_bf16_f32 v98, v186, v188
	v_cvt_pk_bf16_f32 v99, v190, v192
	ds_read_b64_tr_b16 v[100:101], v177 offset:17408
	ds_read_b64_tr_b16 v[102:103], v177 offset:17920
	s_waitcnt lgkmcnt(12)
	v_mfma_f32_32x32x16_bf16 v[48:63], v[140:143], v[96:99], v[48:63]
	ds_read_b64_tr_b16 v[238:239], v177 offset:29696
	ds_read_b64_tr_b16 v[240:241], v177 offset:30208
	v_exp_f32_e32 v179, v104
	v_exp_f32_e32 v181, v105
	v_exp_f32_e32 v183, v106
	v_add_f32_e32 v242, v180, v178
	s_waitcnt lgkmcnt(12)
	v_mfma_f32_32x32x16_bf16 v[32:47], v[136:139], v[96:99], v[32:47]
	v_exp_f32_e32 v185, v107
	v_exp_f32_e32 v187, v108
	v_exp_f32_e32 v189, v109
	v_add_f32_e32 v242, v182, v242
	s_waitcnt lgkmcnt(10)
	v_mfma_f32_32x32x16_bf16 v[16:31], v[132:135], v[96:99], v[16:31]
	v_exp_f32_e32 v191, v110
	v_exp_f32_e32 v193, v111
	v_add_f32_e32 v242, v184, v242
	v_add_f32_e32 v242, v186, v242
	ds_read_b64_tr_b16 v[104:105], v177 offset:18432
	ds_read_b64_tr_b16 v[106:107], v177 offset:18944
	ds_read_b64_tr_b16 v[108:109], v177 offset:19456
	ds_read_b64_tr_b16 v[110:111], v177 offset:19968
	s_waitcnt lgkmcnt(12)
	v_mfma_f32_32x32x16_bf16 v[0:15], v[128:131], v[96:99], v[0:15]
	ds_read_b64_tr_b16 v[128:129], v177 offset:26624
	ds_read_b64_tr_b16 v[130:131], v177 offset:27136
	v_cvt_pk_bf16_f32 v96, v179, v181
	v_cvt_pk_bf16_f32 v97, v183, v185
	v_cvt_pk_bf16_f32 v98, v187, v189
	v_cvt_pk_bf16_f32 v99, v191, v193
	v_exp_f32_e32 v140, v84
	v_exp_f32_e32 v142, v85
	s_waitcnt lgkmcnt(8)
	v_mfma_f32_32x32x16_bf16 v[48:63], v[100:103], v[96:99], v[48:63]
	v_exp_f32_e32 v194, v86
	v_exp_f32_e32 v196, v87
	v_add_f32_e32 v242, v188, v242
	ds_read_b64_tr_b16 v[84:85], v177 offset:22528
	ds_read_b64_tr_b16 v[86:87], v177 offset:23040
	v_exp_f32_e32 v136, v82
	s_waitcnt lgkmcnt(14)
	v_mfma_f32_32x32x16_bf16 v[32:47], v[230:233], v[96:99], v[32:47]
	ds_read_b64_tr_b16 v[230:231], v177 offset:23552
	ds_read_b64_tr_b16 v[232:233], v177 offset:24064
	v_exp_f32_e32 v138, v83
	v_exp_f32_e32 v132, v80
	v_exp_f32_e32 v134, v81
	v_add_f32_e32 v242, v190, v242
	s_waitcnt lgkmcnt(14)
	v_mfma_f32_32x32x16_bf16 v[16:31], v[234:237], v[96:99], v[16:31]
	ds_read_b64_tr_b16 v[234:235], v177 offset:27648
	ds_read_b64_tr_b16 v[236:237], v177 offset:28160
	v_cvt_pk_bf16_f32 v80, v132, v134
	v_cvt_pk_bf16_f32 v81, v136, v138
	v_cvt_pk_bf16_f32 v82, v140, v142
	v_cvt_pk_bf16_f32 v83, v194, v196
	v_exp_f32_e32 v133, v88
	v_exp_f32_e32 v135, v89
	s_waitcnt lgkmcnt(12)
	v_mfma_f32_32x32x16_bf16 v[0:15], v[238:241], v[96:99], v[0:15]
	ds_read_b64_tr_b16 v[238:239], v177 offset:31744
	ds_read_b64_tr_b16 v[240:241], v177 offset:32256
	v_exp_f32_e32 v137, v90
	v_exp_f32_e32 v139, v91
	v_add_f32_e32 v242, v192, v242
	ds_read_b64_tr_b16 v[88:89], v177 offset:30720
	ds_read_b64_tr_b16 v[90:91], v177 offset:31232
	v_exp_f32_e32 v141, v92
	s_waitcnt lgkmcnt(14)
	v_mfma_f32_32x32x16_bf16 v[48:63], v[104:107], v[80:83], v[48:63]
	v_exp_f32_e32 v143, v93
	v_exp_f32_e32 v195, v94
	v_exp_f32_e32 v197, v95
	v_add_f32_e32 v242, v132, v242
	s_waitcnt lgkmcnt(8)
	v_mfma_f32_32x32x16_bf16 v[32:47], v[84:87], v[80:83], v[32:47]
	v_add_f32_e32 v243, v181, v179
	v_add_f32_e32 v242, v134, v242
	v_add_f32_e32 v243, v183, v243
	v_add_f32_e32 v242, v136, v242
	v_add_f32_e32 v243, v185, v243
	v_add_f32_e32 v242, v138, v242
	s_waitcnt lgkmcnt(10)
	v_mfma_f32_32x32x16_bf16 v[16:31], v[128:131], v[80:83], v[16:31]
	v_add_f32_e32 v243, v187, v243
	v_add_f32_e32 v242, v140, v242
	v_add_f32_e32 v243, v189, v243
	v_add_f32_e32 v242, v142, v242
	v_add_f32_e32 v243, v191, v243
	v_add_f32_e32 v242, v194, v242
	v_add_f32_e32 v243, v193, v243
	s_waitcnt lgkmcnt(0)
	v_mfma_f32_32x32x16_bf16 v[0:15], v[88:91], v[80:83], v[0:15]
	v_cvt_pk_bf16_f32 v80, v133, v135
	v_cvt_pk_bf16_f32 v81, v137, v139
	v_cvt_pk_bf16_f32 v82, v141, v143
	v_cvt_pk_bf16_f32 v83, v195, v197
	v_add_f32_e32 v242, v196, v242
	v_add_f32_e32 v243, v133, v243
	s_waitcnt lgkmcnt(12)
	v_mfma_f32_32x32x16_bf16 v[48:63], v[108:111], v[80:83], v[48:63]
	v_add_f32_e32 v243, v135, v243
	v_add_f32_e32 v243, v137, v243
	s_waitcnt lgkmcnt(6)
	v_mfma_f32_32x32x16_bf16 v[32:47], v[230:233], v[80:83], v[32:47]
	v_add_f32_e32 v243, v139, v243
	v_add_f32_e32 v243, v141, v243
	s_waitcnt lgkmcnt(4)
	v_mfma_f32_32x32x16_bf16 v[16:31], v[234:237], v[80:83], v[16:31]
	v_add_f32_e32 v243, v143, v243
	v_add_f32_e32 v243, v195, v243
	s_waitcnt lgkmcnt(2)
	v_mfma_f32_32x32x16_bf16 v[0:15], v[238:241], v[80:83], v[0:15]
	v_add_f32_e32 v243, v197, v243
	v_add_f32_e32 v242, v242, v243
	v_add_f32_e32 v176, v176, v242
